# MLA attention loop: software-pipelined LDS fragment reads in QK and PV phases (3-deep, 4 buffers), removed over-conservative vmcnt(0) before PV
# speedup vs baseline: 1.0005x; 1.0005x over previous
; template <int DQK, int NSUB> ...
;     ...
; #pragma unroll
;       for (int i = 0; i < 4; ++i) {
;         int c = tid + i * 256, r = c >> 3, kc = c & 7;
;         vreg[i] = *(const u32x4*)(Vt + (size_t)r * ldv + k1 + kc * 8);
;       }
;     }
;     f32x4 sacc[4][NSUB];
; #pragma unroll
;     for (int kt = 0; kt < 4; ++kt)
; #pragma unroll
;       for (int sub = 0; sub < NSUB; ++sub) sacc[kt][sub] = (f32x4){0.f, 0.f, 0.f, 0.f};
;     __builtin_amdgcn_s_setprio(1);
; #pragma unroll
;     for (int ks = 0; ks < NKS; ++ks) {
; #pragma unroll
;       for (int kt = 0; kt < 4; ++kt) {
;         bf16x8 kf = *(const bf16x8*)(Ks + (kt * 16 + l15) * LDK + (((ks * 4 + quad) ^ (l15 & SW)) * 8));
; #pragma unroll
;         for (int sub = 0; sub < NSUB; ++sub)
;           sacc[kt][sub] = __builtin_amdgcn_mfma_f32_16x16x32_bf16(kf, qf[sub][ks], sacc[kt][sub], 0, 0, 0);
;       }
;       __builtin_amdgcn_sched_barrier(0);
;     }
;     __builtin_amdgcn_s_setprio(0);
.LBB0_216:
	v_lshl_add_u64 v[112:113], s[96:97], 0, v[180:181]
	v_lshl_add_u64 v[116:117], s[96:97], 0, v[182:183]
	v_lshl_add_u64 v[120:121], s[96:97], 0, v[184:185]
	v_lshl_add_u64 v[124:125], s[96:97], 0, v[186:187]
	global_load_dwordx4 v[112:115], v[112:113], off
	s_nop 0
	global_load_dwordx4 v[116:119], v[116:117], off
	s_nop 0
	global_load_dwordx4 v[120:123], v[120:121], off
	s_nop 0
	global_load_dwordx4 v[124:127], v[124:125], off
	v_mov_b32_e32 v188, v227
	s_setprio 1
	ds_read_b128 v[232:235], v225
	ds_read_b128 v[240:243], v225 offset:6144
	ds_read_b128 v[248:251], v225 offset:12288
	ds_read_b128 v[252:255], v225 offset:18432
	s_waitcnt lgkmcnt(3)
	v_mfma_f32_16x16x32_bf16 v[136:139], v[232:235], v[104:107], 0
	v_mfma_f32_16x16x32_bf16 v[152:155], v[232:235], v[108:111], 0
	ds_read_b128 v[232:235], v224
	s_waitcnt lgkmcnt(3)
	v_mfma_f32_16x16x32_bf16 v[140:143], v[240:243], v[104:107], 0
	v_mfma_f32_16x16x32_bf16 v[156:159], v[240:243], v[108:111], 0
	ds_read_b128 v[240:243], v224 offset:6144
	s_waitcnt lgkmcnt(3)
	v_mfma_f32_16x16x32_bf16 v[128:131], v[248:251], v[104:107], 0
	v_mfma_f32_16x16x32_bf16 v[144:147], v[248:251], v[108:111], 0
	ds_read_b128 v[248:251], v224 offset:12288
	s_waitcnt lgkmcnt(3)
	v_mfma_f32_16x16x32_bf16 v[132:135], v[252:255], v[104:107], 0
	v_mfma_f32_16x16x32_bf16 v[148:151], v[252:255], v[108:111], 0
	ds_read_b128 v[252:255], v224 offset:18432
	s_waitcnt lgkmcnt(3)
	v_mfma_f32_16x16x32_bf16 v[136:139], v[232:235], v[96:99], v[136:139]
	v_mfma_f32_16x16x32_bf16 v[152:155], v[232:235], v[100:103], v[152:155]
	ds_read_b128 v[232:235], v223
	s_waitcnt lgkmcnt(3)
	v_mfma_f32_16x16x32_bf16 v[140:143], v[240:243], v[96:99], v[140:143]
	v_mfma_f32_16x16x32_bf16 v[156:159], v[240:243], v[100:103], v[156:159]
	ds_read_b128 v[240:243], v223 offset:6144
	s_waitcnt lgkmcnt(3)
	v_mfma_f32_16x16x32_bf16 v[128:131], v[248:251], v[96:99], v[128:131]
	v_mfma_f32_16x16x32_bf16 v[144:147], v[248:251], v[100:103], v[144:147]
	ds_read_b128 v[248:251], v223 offset:12288
	s_waitcnt lgkmcnt(3)
	v_mfma_f32_16x16x32_bf16 v[132:135], v[252:255], v[96:99], v[132:135]
	v_mfma_f32_16x16x32_bf16 v[148:151], v[252:255], v[100:103], v[148:151]
	ds_read_b128 v[252:255], v223 offset:18432
	s_waitcnt lgkmcnt(3)
	v_mfma_f32_16x16x32_bf16 v[136:139], v[232:235], v[88:91], v[136:139]
	v_mfma_f32_16x16x32_bf16 v[152:155], v[232:235], v[92:95], v[152:155]
	ds_read_b128 v[232:235], v222
	s_waitcnt lgkmcnt(3)
	v_mfma_f32_16x16x32_bf16 v[140:143], v[240:243], v[88:91], v[140:143]
	v_mfma_f32_16x16x32_bf16 v[156:159], v[240:243], v[92:95], v[156:159]
	ds_read_b128 v[240:243], v222 offset:6144
	s_waitcnt lgkmcnt(3)
	v_mfma_f32_16x16x32_bf16 v[128:131], v[248:251], v[88:91], v[128:131]
	v_mfma_f32_16x16x32_bf16 v[144:147], v[248:251], v[92:95], v[144:147]
	ds_read_b128 v[248:251], v222 offset:12288
	s_waitcnt lgkmcnt(3)
	v_mfma_f32_16x16x32_bf16 v[132:135], v[252:255], v[88:91], v[132:135]
	v_mfma_f32_16x16x32_bf16 v[148:151], v[252:255], v[92:95], v[148:151]
	ds_read_b128 v[252:255], v222 offset:18432
	s_waitcnt lgkmcnt(3)
	v_mfma_f32_16x16x32_bf16 v[136:139], v[232:235], v[80:83], v[136:139]
	v_mfma_f32_16x16x32_bf16 v[152:155], v[232:235], v[84:87], v[152:155]
	ds_read_b128 v[232:235], v217
	s_waitcnt lgkmcnt(3)
	v_mfma_f32_16x16x32_bf16 v[140:143], v[240:243], v[80:83], v[140:143]
	v_mfma_f32_16x16x32_bf16 v[156:159], v[240:243], v[84:87], v[156:159]
	ds_read_b128 v[240:243], v217 offset:6144
	s_waitcnt lgkmcnt(3)
	v_mfma_f32_16x16x32_bf16 v[128:131], v[248:251], v[80:83], v[128:131]
	v_mfma_f32_16x16x32_bf16 v[144:147], v[248:251], v[84:87], v[144:147]
	ds_read_b128 v[248:251], v217 offset:12288
	s_waitcnt lgkmcnt(3)
	v_mfma_f32_16x16x32_bf16 v[132:135], v[252:255], v[80:83], v[132:135]
	v_mfma_f32_16x16x32_bf16 v[148:151], v[252:255], v[84:87], v[148:151]
	ds_read_b128 v[252:255], v217 offset:18432
	s_waitcnt lgkmcnt(3)
	v_mfma_f32_16x16x32_bf16 v[136:139], v[232:235], v[72:75], v[136:139]
	v_mfma_f32_16x16x32_bf16 v[152:155], v[232:235], v[76:79], v[152:155]
	ds_read_b128 v[232:235], v215
	s_waitcnt lgkmcnt(3)
	v_mfma_f32_16x16x32_bf16 v[140:143], v[240:243], v[72:75], v[140:143]
	v_mfma_f32_16x16x32_bf16 v[156:159], v[240:243], v[76:79], v[156:159]
	ds_read_b128 v[240:243], v215 offset:6144
	s_waitcnt lgkmcnt(3)
	v_mfma_f32_16x16x32_bf16 v[128:131], v[248:251], v[72:75], v[128:131]
	v_mfma_f32_16x16x32_bf16 v[144:147], v[248:251], v[76:79], v[144:147]
	ds_read_b128 v[248:251], v215 offset:12288
	s_waitcnt lgkmcnt(3)
	v_mfma_f32_16x16x32_bf16 v[132:135], v[252:255], v[72:75], v[132:135]
	v_mfma_f32_16x16x32_bf16 v[148:151], v[252:255], v[76:79], v[148:151]
	ds_read_b128 v[252:255], v215 offset:18432
	s_waitcnt lgkmcnt(3)
	v_mfma_f32_16x16x32_bf16 v[136:139], v[232:235], v[64:67], v[136:139]
	v_mfma_f32_16x16x32_bf16 v[152:155], v[232:235], v[68:71], v[152:155]
	s_waitcnt lgkmcnt(2)
	v_mfma_f32_16x16x32_bf16 v[140:143], v[240:243], v[64:67], v[140:143]
	v_mfma_f32_16x16x32_bf16 v[156:159], v[240:243], v[68:71], v[156:159]
	s_waitcnt lgkmcnt(1)
	v_mfma_f32_16x16x32_bf16 v[128:131], v[248:251], v[64:67], v[128:131]
	v_mfma_f32_16x16x32_bf16 v[144:147], v[248:251], v[68:71], v[144:147]
	s_waitcnt lgkmcnt(0)
	v_mfma_f32_16x16x32_bf16 v[132:135], v[252:255], v[64:67], v[132:135]
	v_mfma_f32_16x16x32_bf16 v[148:151], v[252:255], v[68:71], v[148:151]
	s_setprio 0
	v_readfirstlane_b32 s24, v221
	v_add_u32_e32 v191, 0x1000, v221
	s_waitcnt lgkmcnt(0)
	s_barrier
; template <int DQK, int NSUB> ...
;     ...
;       if (KDMA) {
; #pragma unroll
;         for (int i = 0; i < 6; ++i)
;           __builtin_amdgcn_global_load_lds((const unsigned*)(K + (size_t)k1 * ldk + koff[i]),
;                                            (unsigned*)((char*)Ks + (w + 4 * i) * 1024), 16, 0, 0);
;       }
;     }
;     __builtin_amdgcn_sched_barrier(0);
;     bf16x8 pf[NSUB][2];
; #pragma unroll
;     for (int sub = 0; sub < NSUB; ++sub) {
;       float mx = -1e30f;
; #pragma unroll
;       for (int kt = 0; kt < 4; ++kt)
; #pragma unroll
;         for (int j = 0; j < 4; ++j) mx = fmaxf(mx, sacc[kt][sub][j]);
;       mx = fmaxf(mx, __shfl_xor(mx, 16));
;       mx = fmaxf(mx, __shfl_xor(mx, 32));
;       float mnew = fmaxf(mrow[sub], mx + cb);
;       float alpha = __builtin_amdgcn_exp2f(mrow[sub] - mnew);
;       mrow[sub] = mnew;
;       const float off = cb - mnew;
;       float ps = 0.f;
;       float pv[4][4];
; #pragma unroll
;       for (int kt = 0; kt < 4; ++kt)
; #pragma unroll
;         for (int j = 0; j < 4; ++j) {
;           pv[kt][j] = __builtin_amdgcn_exp2f(sacc[kt][sub][j] + off);
;           ps += pv[kt][j];
;         }
;       lrow[sub] = lrow[sub] * alpha + ps;
; #pragma unroll
;       for (int kb = 0; kb < 2; ++kb) {
;         u32x4 pu = {pack2(pv[2 * kb][0], pv[2 * kb][1]), pack2(pv[2 * kb][2], pv[2 * kb][3]),
;                     pack2(pv[2 * kb + 1][0], pv[2 * kb + 1][1]), pack2(pv[2 * kb + 1][2], pv[2 * kb + 1][3])};
;         pf[sub][kb] = __builtin_bit_cast(bf16x8, pu);
;       }
;       if (__builtin_amdgcn_ballot_w64(alpha != 1.f) != 0) {
; #pragma unroll
;         for (int et = 0; et < 8; ++et) {
;           oacc[et][sub][0] *= alpha; oacc[et][sub][1] *= alpha;
;           oacc[et][sub][2] *= alpha; oacc[et][sub][3] *= alpha;
;         }
;       }
	v_lshl_add_u64 v[232:233], s[96:97], 0, v[164:165]
	s_mov_b32 m0, s24
	v_readfirstlane_b32 s24, v191
	v_add_u32_e32 v191, 0x2000, v221
	global_load_lds_dwordx4 v[232:233], off
	v_lshl_add_u64 v[232:233], s[96:97], 0, v[166:167]
	s_mov_b32 m0, s24
	v_readfirstlane_b32 s24, v191
	v_add_u32_e32 v191, 0x3000, v221
	global_load_lds_dwordx4 v[232:233], off
	v_lshl_add_u64 v[232:233], s[96:97], 0, v[172:173]
	s_mov_b32 m0, s24
	v_readfirstlane_b32 s24, v191
	v_add_u32_e32 v191, 0x4000, v221
	global_load_lds_dwordx4 v[232:233], off
	v_lshl_add_u64 v[232:233], s[96:97], 0, v[174:175]
	s_mov_b32 m0, s24
	v_readfirstlane_b32 s24, v191
	v_add_u32_e32 v191, 0x5000, v221
	global_load_lds_dwordx4 v[232:233], off
	v_lshl_add_u64 v[232:233], s[96:97], 0, v[176:177]
	s_mov_b32 m0, s24
	v_readfirstlane_b32 s24, v191
	global_load_lds_dwordx4 v[232:233], off
	v_lshl_add_u64 v[232:233], s[96:97], 0, v[178:179]
	s_mov_b32 m0, s24
	s_nop 0
	global_load_lds_dwordx4 v[232:233], off
	v_max3_f32 v214, v136, s27, v137
	v_max3_f32 v214, v214, v138, v139
	v_max3_f32 v214, v214, v140, v141
	v_max3_f32 v214, v214, v142, v143
	v_max3_f32 v214, v214, v128, v129
	v_cmp_lt_i32_e32 vcc, v200, v198
	v_max3_f32 v214, v214, v130, v131
	v_max3_f32 v214, v214, v132, v133
	v_cndmask_b32_e32 v191, v197, v200, vcc
	v_lshlrev_b32_e32 v191, 2, v191
	v_max3_f32 v227, v214, v134, v135
	ds_bpermute_b32 v228, v191, v227
	v_cmp_lt_i32_e32 vcc, v199, v198
	s_waitcnt lgkmcnt(0)
	v_max_f32_e32 v228, v228, v228
	v_cndmask_b32_e32 v214, v197, v199, vcc
	v_lshlrev_b32_e32 v214, 2, v214
	v_max_f32_e32 v227, v227, v228
	ds_bpermute_b32 v228, v214, v227
	s_waitcnt lgkmcnt(0)
	v_max_f32_e32 v228, v228, v228
	v_max_f32_e32 v227, v227, v228
	v_add_f32_e32 v227, 0, v227
	v_max_f32_e32 v228, v188, v188
	v_max_f32_e32 v227, v228, v227
	v_sub_f32_e32 v188, v188, v227
	v_exp_f32_e32 v188, v188
	s_nop 0
	v_cmp_neq_f32_e32 vcc, 1.0, v188
	s_cbranch_vccz .LBB0_218
	v_pk_mul_f32 v[62:63], v[62:63], v[188:189] op_sel_hi:[1,0]
	v_pk_mul_f32 v[60:61], v[60:61], v[188:189] op_sel_hi:[1,0]
	v_pk_mul_f32 v[54:55], v[54:55], v[188:189] op_sel_hi:[1,0]
	v_pk_mul_f32 v[52:53], v[52:53], v[188:189] op_sel_hi:[1,0]
	v_pk_mul_f32 v[46:47], v[46:47], v[188:189] op_sel_hi:[1,0]
	v_pk_mul_f32 v[44:45], v[44:45], v[188:189] op_sel_hi:[1,0]
	v_pk_mul_f32 v[38:39], v[38:39], v[188:189] op_sel_hi:[1,0]
	v_pk_mul_f32 v[36:37], v[36:37], v[188:189] op_sel_hi:[1,0]
	v_pk_mul_f32 v[30:31], v[30:31], v[188:189] op_sel_hi:[1,0]
	v_pk_mul_f32 v[28:29], v[28:29], v[188:189] op_sel_hi:[1,0]
	v_pk_mul_f32 v[22:23], v[22:23], v[188:189] op_sel_hi:[1,0]
	v_pk_mul_f32 v[20:21], v[20:21], v[188:189] op_sel_hi:[1,0]
	v_pk_mul_f32 v[14:15], v[14:15], v[188:189] op_sel_hi:[1,0]
	v_pk_mul_f32 v[12:13], v[12:13], v[188:189] op_sel_hi:[1,0]
	v_pk_mul_f32 v[10:11], v[10:11], v[188:189] op_sel_hi:[1,0]
	v_pk_mul_f32 v[8:9], v[8:9], v[188:189] op_sel_hi:[1,0]

; template <int DQK, int NSUB> ...
;     ...
;       const float off = cb - mnew;
;       float ps = 0.f;
;       float pv[4][4];
; #pragma unroll
;       for (int kt = 0; kt < 4; ++kt)
; #pragma unroll
;         for (int j = 0; j < 4; ++j) {
;           pv[kt][j] = __builtin_amdgcn_exp2f(sacc[kt][sub][j] + off);
;           ps += pv[kt][j];
;         }
;       lrow[sub] = lrow[sub] * alpha + ps;
; #pragma unroll
;       for (int kb = 0; kb < 2; ++kb) {
;         u32x4 pu = {pack2(pv[2 * kb][0], pv[2 * kb][1]), pack2(pv[2 * kb][2], pv[2 * kb][3]),
;                     pack2(pv[2 * kb + 1][0], pv[2 * kb + 1][1]), pack2(pv[2 * kb + 1][2], pv[2 * kb + 1][3])};
;         pf[sub][kb] = __builtin_bit_cast(bf16x8, pu);
;       }
;       if (__builtin_amdgcn_ballot_w64(alpha != 1.f) != 0) {
; #pragma unroll
;         for (int et = 0; et < 8; ++et) {
;           oacc[et][sub][0] *= alpha; oacc[et][sub][1] *= alpha;
;           oacc[et][sub][2] *= alpha; oacc[et][sub][3] *= alpha;
;         }
;       }
;     }
;     __builtin_amdgcn_s_setprio(1);
; #pragma unroll
;     for (int et = 0; et < 8; ++et) {
; #pragma unroll
;       for (int kb = 0; kb < 2; ++kb) {
;         const u16* vp = Vs + (et * 16 + l15) * 72 + kb * 32 + quad * 4;
;         u32x2 a0 = *(const u32x2*)vp;
;         u32x2 a1 = *(const u32x2*)(vp + 16);
;         u32x4 cu = {a0.x, a0.y, a1.x, a1.y};
;         bf16x8 vb = __builtin_bit_cast(bf16x8, cu);
; #pragma unroll
.LBB0_220:
	v_add_f32_e64 v152, v152, -v228
	v_exp_f32_e32 v152, v152
	v_add_f32_e64 v153, v153, -v228
	v_exp_f32_e32 v153, v153
	v_add_f32_e64 v154, v154, -v228
	v_exp_f32_e32 v154, v154
	v_add_f32_e64 v155, v155, -v228
	v_exp_f32_e32 v155, v155
	v_add_f32_e64 v156, v156, -v228
	v_add_f32_e32 v231, 0, v152
	v_exp_f32_e32 v156, v156
	v_add_f32_e64 v157, v157, -v228
	v_add_f32_e32 v231, v153, v231
	v_exp_f32_e32 v157, v157
	v_add_f32_e64 v158, v158, -v228
	v_add_f32_e32 v231, v154, v231
	v_exp_f32_e32 v158, v158
	v_add_f32_e64 v159, v159, -v228
	v_add_f32_e32 v231, v155, v231
	v_exp_f32_e32 v159, v159
	v_add_f32_e64 v144, v144, -v228
	v_add_f32_e32 v231, v156, v231
	v_exp_f32_e32 v232, v144
	v_add_f32_e64 v144, v145, -v228
	v_add_f32_e32 v231, v157, v231
	v_exp_f32_e32 v145, v144
	v_add_f32_e32 v231, v158, v231
	v_add_f32_e64 v144, v146, -v228
	v_add_f32_e64 v136, v136, -v227
	v_add_f32_e32 v231, v159, v231
	v_exp_f32_e32 v233, v144
	v_add_f32_e64 v144, v147, -v228
	v_add_f32_e64 v146, v148, -v228
	v_exp_f32_e32 v136, v136
	v_add_f32_e64 v137, v137, -v227
	v_exp_f32_e32 v234, v144
	v_add_f32_e32 v144, v232, v231
	v_exp_f32_e32 v231, v146
	v_add_f32_e64 v146, v149, -v228
	v_exp_f32_e32 v137, v137
	v_add_f32_e64 v138, v138, -v227
	v_add_f32_e32 v144, v145, v144
	v_exp_f32_e32 v235, v146
	v_add_f32_e64 v146, v150, -v228
	v_cvt_pk_bf16_f32 v150, v232, v145
	v_exp_f32_e32 v145, v138
	v_add_f32_e64 v138, v139, -v227
	v_exp_f32_e32 v139, v138
	v_add_f32_e64 v140, v140, -v227
	v_add_f32_e32 v138, 0, v136
	v_exp_f32_e32 v140, v140
	v_add_f32_e64 v141, v141, -v227
	v_add_f32_e32 v138, v137, v138
	v_exp_f32_e32 v141, v141
	v_add_f32_e64 v142, v142, -v227
	v_add_f32_e32 v138, v145, v138
	v_exp_f32_e32 v142, v142
	v_add_f32_e64 v143, v143, -v227
	v_add_f32_e32 v138, v139, v138
	v_exp_f32_e32 v143, v143
	v_add_f32_e64 v128, v128, -v227
	v_cvt_pk_bf16_f32 v147, v154, v155
	v_add_f32_e32 v138, v140, v138
	v_exp_f32_e32 v154, v128
	v_add_f32_e64 v128, v129, -v227
	v_add_f32_e32 v138, v141, v138
	v_exp_f32_e32 v129, v128
	v_add_f32_e64 v128, v130, -v227
	v_add_f32_e32 v138, v142, v138
	v_exp_f32_e32 v130, v128
	v_add_f32_e64 v128, v131, -v227
	v_add_f32_e32 v138, v143, v138
	v_exp_f32_e32 v131, v128
	v_add_f32_e64 v132, v132, -v227
	v_add_f32_e32 v128, v154, v138
	v_exp_f32_e32 v132, v132
	v_add_f32_e64 v133, v133, -v227
	v_add_f32_e32 v128, v129, v128
	v_exp_f32_e32 v133, v133
	v_add_f32_e64 v134, v134, -v227
	v_add_f32_e32 v144, v233, v144
	v_exp_f32_e32 v240, v146
	v_add_f32_e64 v146, v151, -v228
	v_add_f32_e32 v128, v130, v128
	v_exp_f32_e32 v134, v134
	v_add_f32_e64 v135, v135, -v227
	v_add_f32_e32 v144, v234, v144
	v_exp_f32_e32 v241, v146
	v_add_f32_e32 v128, v131, v128
	v_exp_f32_e32 v135, v135
	v_add_f32_e32 v144, v231, v144
	v_add_f32_e32 v128, v132, v128
	v_add_f32_e32 v144, v235, v144
	v_add_f32_e32 v128, v133, v128
	v_add_f32_e32 v144, v240, v144
	v_add_f32_e32 v128, v134, v128
	v_add_f32_e32 v144, v241, v144
	v_add_f32_e32 v128, v135, v128
	v_fmac_f32_e32 v144, v230, v190
	v_fmac_f32_e32 v128, v229, v188
	v_cvt_pk_bf16_f32 v146, v152, v153
	v_cvt_pk_bf16_f32 v148, v156, v157
	v_cvt_pk_bf16_f32 v149, v158, v159
	v_cvt_pk_bf16_f32 v151, v233, v234
	v_cvt_pk_bf16_f32 v152, v231, v235
	v_cvt_pk_bf16_f32 v153, v240, v241
	v_cvt_pk_bf16_f32 v138, v136, v137
	v_cvt_pk_bf16_f32 v139, v145, v139
	v_cvt_pk_bf16_f32 v140, v140, v141
	v_cvt_pk_bf16_f32 v141, v142, v143
	v_cvt_pk_bf16_f32 v154, v154, v129
	v_cvt_pk_bf16_f32 v155, v130, v131
	v_cvt_pk_bf16_f32 v156, v132, v133
	v_cvt_pk_bf16_f32 v157, v134, v135
	s_setprio 1
	v_add_u32_e32 v131, 0x6000, v226
	v_add_u32_e32 v129, 0x6800, v226
	v_add_u32_e32 v134, 0x7000, v226
	v_add_u32_e32 v130, 0x7800, v226
	v_add_u32_e32 v135, 0x8800, v226
	v_add_u32_e32 v132, 0x9000, v226
	v_add_u32_e32 v136, 0x9800, v226
	v_add_u32_e32 v133, 0xa000, v226
	ds_read2_b64 v[232:235], v131 offset0:128 offset1:132
	ds_read2_b64 v[240:243], v131 offset0:136 offset1:140
	ds_read2_b64 v[248:251], v129 offset0:160 offset1:164
	ds_read2_b64 v[252:255], v129 offset0:168 offset1:172
	s_waitcnt lgkmcnt(3)
; #define LBAR() asm volatile("s_waitcnt lgkmcnt(0)\n\ts_barrier" ::: "memory")
; template <int DQK, int NSUB> ...
;     ...
; #pragma unroll
;     for (int et = 0; et < 8; ++et) {
; #pragma unroll
;       for (int kb = 0; kb < 2; ++kb) {
;         const u16* vp = Vs + (et * 16 + l15) * 72 + kb * 32 + quad * 4;
;         u32x2 a0 = *(const u32x2*)vp;
;         u32x2 a1 = *(const u32x2*)(vp + 16);
;         u32x4 cu = {a0.x, a0.y, a1.x, a1.y};
;         bf16x8 vb = __builtin_bit_cast(bf16x8, cu);
; #pragma unroll
;         for (int sub = 0; sub < NSUB; ++sub)
;           oacc[et][sub] = __builtin_amdgcn_mfma_f32_16x16x32_bf16(vb, pf[sub][kb], oacc[et][sub], 0, 0, 0);
;       }
;       if (et & 1) __builtin_amdgcn_sched_barrier(0);
;     }
;     __builtin_amdgcn_s_setprio(0);
;     if (more) {
;       if (KDMA) {
;         asm volatile("s_waitcnt vmcnt(0)" ::: "memory");
;       } else {
; #pragma unroll
;         for (int i = 0; i < NKC; ++i) {
;           int c = tid + i * 256, r = c / (DQK / 8), kc = c % (DQK / 8);
;           *(u32x4*)(Ks + r * LDK + ((kc ^ (r & SW)) * 8)) = kreg[i];
;         }
;       }
;     }
;     LBAR();
;     if (more) {
; #pragma unroll
;       for (int i = 0; i < 4; ++i) {
;         int c = tid + i * 256, r = c >> 3, kc = c & 7;
;         *(u32x4*)(Vs + r * 72 + kc * 8) = vreg[i];
;       }
;     }
	v_mfma_f32_16x16x32_bf16 v[60:63], v[232:235], v[138:141], v[60:63]
	v_mfma_f32_16x16x32_bf16 v[56:59], v[232:235], v[146:149], v[56:59]
	ds_read2_b64 v[232:235], v134 offset0:192 offset1:196
	s_waitcnt lgkmcnt(3)
	v_mfma_f32_16x16x32_bf16 v[60:63], v[240:243], v[154:157], v[60:63]
	v_mfma_f32_16x16x32_bf16 v[56:59], v[240:243], v[150:153], v[56:59]
	ds_read2_b64 v[240:243], v134 offset0:200 offset1:204
	s_waitcnt lgkmcnt(3)
	v_mfma_f32_16x16x32_bf16 v[52:55], v[248:251], v[138:141], v[52:55]
	v_mfma_f32_16x16x32_bf16 v[48:51], v[248:251], v[146:149], v[48:51]
	ds_read2_b64 v[248:251], v130 offset0:224 offset1:228
	s_waitcnt lgkmcnt(3)
	v_mfma_f32_16x16x32_bf16 v[52:55], v[252:255], v[154:157], v[52:55]
	v_mfma_f32_16x16x32_bf16 v[48:51], v[252:255], v[150:153], v[48:51]
	ds_read2_b64 v[252:255], v130 offset0:232 offset1:236
	s_waitcnt lgkmcnt(3)
	v_mfma_f32_16x16x32_bf16 v[44:47], v[232:235], v[138:141], v[44:47]
	v_mfma_f32_16x16x32_bf16 v[40:43], v[232:235], v[146:149], v[40:43]
	ds_read2_b64 v[232:235], v135 offset1:4
	s_waitcnt lgkmcnt(3)
	v_mfma_f32_16x16x32_bf16 v[44:47], v[240:243], v[154:157], v[44:47]
	v_mfma_f32_16x16x32_bf16 v[40:43], v[240:243], v[150:153], v[40:43]
	ds_read2_b64 v[240:243], v135 offset0:8 offset1:12
	s_waitcnt lgkmcnt(3)
	v_mfma_f32_16x16x32_bf16 v[36:39], v[248:251], v[138:141], v[36:39]
	v_mfma_f32_16x16x32_bf16 v[32:35], v[248:251], v[146:149], v[32:35]
	ds_read2_b64 v[248:251], v132 offset0:32 offset1:36
	s_waitcnt lgkmcnt(3)
	v_mfma_f32_16x16x32_bf16 v[36:39], v[252:255], v[154:157], v[36:39]
	v_mfma_f32_16x16x32_bf16 v[32:35], v[252:255], v[150:153], v[32:35]
	ds_read2_b64 v[252:255], v132 offset0:40 offset1:44
	s_waitcnt lgkmcnt(3)
	v_mfma_f32_16x16x32_bf16 v[28:31], v[232:235], v[138:141], v[28:31]
	v_mfma_f32_16x16x32_bf16 v[24:27], v[232:235], v[146:149], v[24:27]
	ds_read2_b64 v[232:235], v136 offset0:64 offset1:68
	s_waitcnt lgkmcnt(3)
	v_mfma_f32_16x16x32_bf16 v[28:31], v[240:243], v[154:157], v[28:31]
	v_mfma_f32_16x16x32_bf16 v[24:27], v[240:243], v[150:153], v[24:27]
	ds_read2_b64 v[240:243], v136 offset0:72 offset1:76
	s_waitcnt lgkmcnt(3)
	v_mfma_f32_16x16x32_bf16 v[20:23], v[248:251], v[138:141], v[20:23]
	v_mfma_f32_16x16x32_bf16 v[16:19], v[248:251], v[146:149], v[16:19]
	ds_read2_b64 v[248:251], v133 offset0:96 offset1:100
	s_waitcnt lgkmcnt(3)
	v_mfma_f32_16x16x32_bf16 v[20:23], v[252:255], v[154:157], v[20:23]
	v_mfma_f32_16x16x32_bf16 v[16:19], v[252:255], v[150:153], v[16:19]
	ds_read2_b64 v[252:255], v133 offset0:104 offset1:108
	s_waitcnt lgkmcnt(3)
	v_mfma_f32_16x16x32_bf16 v[12:15], v[232:235], v[138:141], v[12:15]
	v_mfma_f32_16x16x32_bf16 v[0:3], v[232:235], v[146:149], v[0:3]
	s_waitcnt lgkmcnt(2)
	v_mfma_f32_16x16x32_bf16 v[12:15], v[240:243], v[154:157], v[12:15]
	v_mfma_f32_16x16x32_bf16 v[0:3], v[240:243], v[150:153], v[0:3]
	s_waitcnt lgkmcnt(1)
	v_mfma_f32_16x16x32_bf16 v[8:11], v[248:251], v[138:141], v[8:11]
	v_mfma_f32_16x16x32_bf16 v[4:7], v[248:251], v[146:149], v[4:7]
	s_waitcnt lgkmcnt(0)
	v_mfma_f32_16x16x32_bf16 v[8:11], v[252:255], v[154:157], v[8:11]
	v_mfma_f32_16x16x32_bf16 v[4:7], v[252:255], v[150:153], v[4:7]
	s_setprio 0
	s_waitcnt vmcnt(0)
	s_waitcnt lgkmcnt(0)
	s_barrier
	s_add_i32 s30, s30, -1
	v_lshl_add_u64 v[164:165], v[164:165], 0, s[80:81]
	v_lshl_add_u64 v[166:167], v[166:167], 0, s[80:81]
	v_lshl_add_u64 v[172:173], v[172:173], 0, s[80:81]
	v_lshl_add_u64 v[174:175], v[174:175], 0, s[80:81]
	v_lshl_add_u64 v[176:177], v[176:177], 0, s[80:81]
	v_lshl_add_u64 v[178:179], v[178:179], 0, s[80:81]
	v_lshl_add_u64 v[180:181], v[180:181], 0, s[82:83]
	v_lshl_add_u64 v[182:183], v[182:183], 0, s[82:83]
	v_lshl_add_u64 v[184:185], v[184:185], 0, s[82:83]
	s_cmp_eq_u32 s30, 0
	v_lshl_add_u64 v[186:187], v[186:187], 0, s[82:83]
	ds_write_b128 v216, v[112:115] offset:25600
	ds_write_b128 v218, v[116:119] offset:25600
	ds_write_b128 v219, v[120:123] offset:25600
	ds_write_b128 v220, v[124:127] offset:25600
	s_cbranch_scc1 .LBB0_222
	v_mov_b32_e32 v190, v228
	v_mov_b32_e32 v230, v144
	v_mov_b32_e32 v229, v128
	s_branch .LBB0_216

; __global__ void __launch_bounds__(256, 2) mega(Params p, int ph_lo, int ph_hi) {
	.amdhsa_kernel _Z4mega6Paramsii
		.amdhsa_group_segment_fixed_size 49180
		.amdhsa_private_segment_fixed_size 0
		.amdhsa_kernarg_size 520
		.amdhsa_user_sgpr_count 2
		.amdhsa_user_sgpr_dispatch_ptr 0
		.amdhsa_user_sgpr_queue_ptr 0
		.amdhsa_user_sgpr_kernarg_segment_ptr 1
		.amdhsa_user_sgpr_dispatch_id 0
		.amdhsa_user_sgpr_kernarg_preload_length 0
		.amdhsa_user_sgpr_kernarg_preload_offset 0
		.amdhsa_user_sgpr_private_segment_size 0
		.amdhsa_uses_dynamic_stack 0
		.amdhsa_enable_private_segment 0
		.amdhsa_system_sgpr_workgroup_id_x 1
		.amdhsa_system_sgpr_workgroup_id_y 0
		.amdhsa_system_sgpr_workgroup_id_z 0
		.amdhsa_system_sgpr_workgroup_info 0
		.amdhsa_system_vgpr_workitem_id 2
		.amdhsa_next_free_vgpr 256
		.amdhsa_next_free_sgpr 100
		.amdhsa_accum_offset 256
		.amdhsa_reserve_vcc 1
		.amdhsa_float_round_mode_32 0
		.amdhsa_float_round_mode_16_64 0
		.amdhsa_float_denorm_mode_32 3
		.amdhsa_float_denorm_mode_16_64 3
		.amdhsa_dx10_clamp 1
		.amdhsa_ieee_mode 1
		.amdhsa_fp16_overflow 0
		.amdhsa_tg_split 0
		.amdhsa_exception_fp_ieee_invalid_op 0
		.amdhsa_exception_fp_denorm_src 0
		.amdhsa_exception_fp_ieee_div_zero 0
		.amdhsa_exception_fp_ieee_overflow 0
		.amdhsa_exception_fp_ieee_underflow 0
		.amdhsa_exception_fp_ieee_inexact 0
		.amdhsa_exception_int_div_zero 0
	.end_amdhsa_kernel

; __global__ void __launch_bounds__(256, 2) mega(Params p, int ph_lo, int ph_hi) {
amdhsa.kernels:
  - .agpr_count:     0
    .args:
      - .offset:         0
        .size:           256
        .value_kind:     by_value
      - .offset:         256
        .size:           4
        .value_kind:     by_value
      - .offset:         260
        .size:           4
        .value_kind:     by_value
      - .offset:         264
        .size:           4
        .value_kind:     hidden_block_count_x
      - .offset:         268
        .size:           4
        .value_kind:     hidden_block_count_y
      - .offset:         272
        .size:           4
        .value_kind:     hidden_block_count_z
      - .offset:         276
        .size:           2
        .value_kind:     hidden_group_size_x
      - .offset:         278
        .size:           2
        .value_kind:     hidden_group_size_y
      - .offset:         280
        .size:           2
        .value_kind:     hidden_group_size_z
      - .offset:         282
        .size:           2
        .value_kind:     hidden_remainder_x
      - .offset:         284
        .size:           2
        .value_kind:     hidden_remainder_y
      - .offset:         286
        .size:           2
        .value_kind:     hidden_remainder_z
      - .offset:         304
        .size:           8
        .value_kind:     hidden_global_offset_x
      - .offset:         312
        .size:           8
        .value_kind:     hidden_global_offset_y
      - .offset:         320
        .size:           8
        .value_kind:     hidden_global_offset_z
      - .offset:         328
        .size:           2
        .value_kind:     hidden_grid_dims
      - .offset:         352
        .size:           8
        .value_kind:     hidden_multigrid_sync_arg
    .group_segment_fixed_size: 49180
    .kernarg_segment_align: 8
    .kernarg_segment_size: 520
    .language:       OpenCL C
    .language_version:
      - 2
      - 0
    .max_flat_workgroup_size: 256
    .name:           _Z4mega6Paramsii
    .private_segment_fixed_size: 0
    .sgpr_count:     106
    .sgpr_spill_count: 258
    .symbol:         _Z4mega6Paramsii.kd
    .uniform_work_group_size: 1
    .uses_dynamic_stack: false
    .vgpr_count:     256
    .vgpr_spill_count: 0
    .wavefront_size: 64
